# decode_finish: first q.k reduction sunk below the second load batch, lambda arithmetic deferred behind the partial loads (two dependent round trips fewer at the start of the output-projection phase)
# baseline (speedup 1.0000x reference)
.LBB0_648:
	s_mov_b64 s[46:47], s[96:97]
	s_waitcnt lgkmcnt(0)
	s_barrier
	s_load_dwordx4 s[16:19], s[46:47], 0xd8
	s_add_u32 s42, s0, 0x28000
	s_addc_u32 s43, s1, 0
	s_lshl_b32 s35, s2, 3
	s_add_i32 s40, s93, s35
	s_cmp_lt_i32 s2, 64
	s_cbranch_scc0 .LBB0_662
	v_mbcnt_lo_u32_b32 v0, -1, 0
	v_mbcnt_hi_u32_b32 v0, -1, v0
	s_cmpk_gt_i32 s40, 0x1ff
	v_add_u32_e32 v0, s73, v0
	s_load_dwordx8 s[8:15], s[46:47], 0x50
	s_load_dwordx2 s[6:7], s[46:47], 0x70
	v_and_b32_e32 v5, 63, v0
	v_lshlrev_b32_e32 v0, 2, v5
	s_waitcnt lgkmcnt(0)
	global_load_dword v87, v0, s[8:9]
	global_load_dword v88, v0, s[10:11]
	global_load_dword v89, v0, s[12:13]
	global_load_dword v90, v0, s[14:15]
	s_cbranch_scc1 .LBB0_657
	v_lshlrev_b32_e32 v10, 3, v5
	s_waitcnt lgkmcnt(0)
	global_load_dwordx2 v[2:3], v10, s[6:7]
	s_add_u32 s14, s18, 0x29300000
	s_addc_u32 s15, s19, 0
	s_add_u32 s24, s18, 0x29400000
	v_mov_b32_e32 v1, 0
	s_addc_u32 s25, s19, 0
	s_add_u32 s26, s18, 0x8000000
	v_lshl_add_u64 v[6:7], s[16:17], 0, v[0:1]
	s_mov_b64 s[6:7], 0x80f8000
	v_mov_b32_e32 v11, v1
	s_addc_u32 s27, s19, 0
	v_lshl_add_u64 v[6:7], v[6:7], 0, s[6:7]
	v_lshl_add_u64 v[10:11], s[16:17], 0, v[10:11]
	s_mov_b64 s[6:7], 0x8138000
	s_bfe_u32 s28, s75, 0x20006
	v_lshl_add_u64 v[10:11], v[10:11], 0, s[6:7]
	s_sub_i32 s6, 0, s28
	s_cmp_eq_u32 s28, 0
	v_cvt_f32_i32_e32 v9, s6
	s_cselect_b64 s[6:7], -1, 0
	s_sub_i32 s8, 1, s28
	s_cmp_lt_u32 s28, 2
	v_cvt_f32_i32_e32 v23, s8
	s_cselect_b64 s[8:9], -1, 0
	s_sub_i32 s10, 2, s28
	v_cvt_f32_i32_e32 v28, s10
	s_cmp_eq_u32 s28, 3
	v_lshlrev_b32_e32 v8, 1, v5
	s_cselect_b64 s[10:11], -1, 0
	s_xor_b32 s12, s28, 3
	s_mov_b32 s21, 0
	v_cvt_f32_ubyte0_e32 v29, s12
	s_or_b32 s29, s28, 4
	v_mov_b32_e32 v30, 0xff800000
	v_lshlrev_b32_e32 v31, 2, v8
	v_mov_b32_e32 v32, 0x358637bd
	s_mov_b32 s30, 0xf800000
	v_mov_b32_e32 v33, 0x260
	s_mov_b32 s31, 0x3f4ccccd
	s_movk_i32 s41, 0x7fff
	s_mov_b32 s72, 0xffff0000
	v_mov_b32_e32 v34, 0x3bb8aa3b
	v_mov_b32_e32 v35, 0x3cb8aa3b
	v_mov_b32_e32 v36, 1
	s_mov_b32 s75, s40
	s_branch .LBB0_652
.LBB0_651:
	s_ashr_i32 s45, s75, 2
	s_and_b32 s22, s45, -4
	s_or_b32 s16, s22, s28
	s_ashr_i32 s17, s16, 31
	s_lshl_b64 s[12:13], s[16:17], 11
	s_add_u32 s12, s14, s12
	s_addc_u32 s13, s15, s13
	s_lshl_b32 s20, s76, 9
	s_add_u32 s52, s12, s20
	s_addc_u32 s53, s13, 0
	s_ashr_i32 s23, s22, 31
	v_lshl_add_u64 v[20:21], v[6:7], 0, s[20:21]
	s_lshl_b64 s[12:13], s[22:23], 11
	v_lshl_add_u64 v[14:15], v[20:21], 0, s[12:13]
	global_load_dword v22, v0, s[52:53]
	global_load_dword v24, v[14:15], off
	s_or_b32 s17, s22, s76
	s_or_b32 s44, s22, 1
	s_or_b32 s48, s22, 2
	s_or_b32 s50, s45, 3
	s_lshl_b32 s54, s17, 3
	s_ashr_i32 s45, s44, 31
	s_ashr_i32 s49, s48, 31
	s_ashr_i32 s51, s50, 31
	s_ashr_i32 s55, s54, 31
	s_lshl_b64 s[22:23], s[44:45], 11
	s_lshl_b64 s[44:45], s[48:49], 11
	s_lshl_b64 s[48:49], s[50:51], 11
	s_lshl_b64 s[50:51], s[54:55], 3
	v_lshl_add_u64 v[12:13], v[10:11], 0, s[20:21]
	s_or_b32 s20, s50, s28
	s_mul_i32 s17, s51, 0x210
	s_mul_hi_u32 s51, s20, 0x210
	s_mulk_i32 s20, 0x210
	s_add_i32 s51, s51, s17
	s_add_u32 s68, s24, s20
	s_addc_u32 s69, s25, s51
	s_or_b32 s56, s54, 1
	s_ashr_i32 s57, s56, 31
	s_lshl_b64 s[66:67], s[56:57], 3
	s_or_b32 s20, s66, s28
	s_mulk_i32 s67, 0x210
	s_mul_hi_u32 s51, s20, 0x210
	s_mulk_i32 s20, 0x210
	s_add_i32 s51, s51, s67
	s_add_u32 s70, s24, s20
	s_addc_u32 s71, s25, s51
	s_or_b32 s56, s54, 2
	s_ashr_i32 s57, s56, 31
	s_lshl_b64 s[56:57], s[56:57], 3
	v_lshl_add_u64 v[16:17], v[20:21], 0, s[22:23]
	s_or_b32 s51, s56, s28
	v_lshl_add_u64 v[18:19], v[20:21], 0, s[44:45]
	v_lshl_add_u64 v[20:21], v[20:21], 0, s[48:49]
	global_load_dword v25, v[16:17], off
	global_load_dword v26, v[18:19], off
	global_load_dword v27, v[20:21], off
	global_load_dword v62, v[20:21], off offset:256
	global_load_dword v63, v[18:19], off offset:256
	global_load_dword v64, v[16:17], off offset:256
	global_load_dword v65, v[14:15], off offset:256
	s_nop 0
	global_load_dwordx2 v[14:15], v1, s[68:69]
	global_load_dwordx2 v[16:17], v1, s[70:71]
	global_load_dword v66, v0, s[52:53] offset:256
	s_mul_i32 s20, s57, 0x210
	s_mul_hi_u32 s52, s51, 0x210
	s_mulk_i32 s51, 0x210
	s_add_i32 s53, s52, s20
	s_add_u32 s52, s24, s51
	s_addc_u32 s53, s25, s53
	s_or_b32 s58, s54, 3
	s_ashr_i32 s59, s58, 31
	s_lshl_b64 s[58:59], s[58:59], 3
	s_or_b32 s51, s58, s28
	s_mul_i32 s57, s59, 0x210
	s_mul_hi_u32 s55, s51, 0x210
	s_mulk_i32 s51, 0x210
	s_add_i32 s55, s55, s57
	s_add_u32 s80, s24, s51
	s_addc_u32 s81, s25, s55
	s_or_b32 s60, s54, 4
	s_ashr_i32 s61, s60, 31
	s_lshl_b64 s[60:61], s[60:61], 3
	s_or_b32 s51, s60, s28
	s_mul_i32 s59, s61, 0x210
	s_mul_hi_u32 s55, s51, 0x210
	s_mulk_i32 s51, 0x210
	s_add_i32 s55, s55, s59
	s_add_u32 s82, s24, s51
	s_addc_u32 s83, s25, s55
	s_or_b32 s62, s54, 5
	s_ashr_i32 s63, s62, 31
	s_lshl_b64 s[62:63], s[62:63], 3
	s_or_b32 s51, s62, s28
	s_mul_hi_u32 s55, s51, 0x210
	s_mul_i32 s61, s63, 0x210
	s_add_i32 s55, s55, s61
	s_mulk_i32 s51, 0x210
	s_add_u32 s84, s24, s51
	s_addc_u32 s85, s25, s55
	s_or_b32 s64, s54, 6
	s_ashr_i32 s65, s64, 31
	s_lshl_b64 s[64:65], s[64:65], 3
	s_or_b32 s51, s64, s28
	s_mul_hi_u32 s55, s51, 0x210
	s_mul_i32 s63, s65, 0x210
	s_add_i32 s55, s55, s63
	s_mulk_i32 s51, 0x210
	s_add_u32 s86, s24, s51
	s_addc_u32 s87, s25, s55
	s_or_b32 s54, s54, 7
	s_ashr_i32 s55, s54, 31
	s_lshl_b64 s[54:55], s[54:55], 3
	s_or_b32 s51, s54, s28
	s_mul_hi_u32 s65, s51, 0x210
	s_mulk_i32 s55, 0x210
	s_add_i32 s65, s65, s55
	s_mulk_i32 s51, 0x210
	global_load_dwordx2 v[18:19], v1, s[52:53]
	global_load_dwordx2 v[20:21], v1, s[80:81]
	global_load_dwordx2 v[38:39], v1, s[82:83]
	global_load_dwordx2 v[40:41], v1, s[84:85]
	s_add_u32 s88, s24, s51
	s_addc_u32 s89, s25, s65
	global_load_dwordx2 v[42:43], v1, s[86:87]
	global_load_dwordx2 v[44:45], v1, s[88:89]
	global_load_dwordx2 v[46:47], v31, s[68:69] offset:16
	global_load_dwordx2 v[48:49], v31, s[70:71] offset:16
	global_load_dwordx2 v[50:51], v31, s[52:53] offset:16
	global_load_dwordx2 v[52:53], v31, s[80:81] offset:16
	global_load_dwordx2 v[54:55], v31, s[82:83] offset:16
	global_load_dwordx2 v[56:57], v31, s[84:85] offset:16
	global_load_dwordx2 v[58:59], v31, s[86:87] offset:16
	global_load_dwordx2 v[60:61], v31, s[88:89] offset:16
	s_waitcnt vmcnt(24)
	v_mul_f32_e32 v84, v22, v24
	s_nop 1
	v_mov_b32_dpp v84, v84 quad_perm:[1,0,3,2] row_mask:0xf bank_mask:0xf bound_ctrl:1
	v_fmac_f32_e32 v84, v22, v24
	s_nop 1
	v_add_f32_dpp v84, v84, v84 quad_perm:[2,3,0,1] row_mask:0xf bank_mask:0xf bound_ctrl:1
	s_nop 1
	v_add_f32_dpp v84, v84, v84 row_half_mirror row_mask:0xf bank_mask:0xf bound_ctrl:1
	s_nop 1
	v_add_f32_dpp v84, v84, v84 row_ror:8 row_mask:0xf bank_mask:0xf bound_ctrl:1
	v_mov_b32_e32 v85, v84
	s_nop 1
	v_permlane16_swap_b32_e32 v84, v85
	v_add_f32_e32 v24, v84, v85
	v_mov_b32_e32 v86, v24
	s_nop 1
	v_permlane32_swap_b32_e32 v24, v86
	v_add_f32_e32 v67, v24, v86
	v_mul_f32_e32 v91, v87, v88
	s_nop 1
	v_mov_b32_dpp v91, v91 quad_perm:[1,0,3,2] row_mask:0xf bank_mask:0xf bound_ctrl:1
	v_mul_f32_e32 v92, v89, v90
	v_fmac_f32_e32 v91, v87, v88
	s_nop 1
	v_mov_b32_dpp v92, v92 quad_perm:[1,0,3,2] row_mask:0xf bank_mask:0xf bound_ctrl:1
	v_fmac_f32_e32 v92, v89, v90
	s_nop 1
	v_add_f32_dpp v94, v91, v91 quad_perm:[2,3,0,1] row_mask:0xf bank_mask:0xf bound_ctrl:1
	s_nop 1
	v_add_f32_dpp v95, v92, v92 quad_perm:[2,3,0,1] row_mask:0xf bank_mask:0xf bound_ctrl:1
	s_nop 1
	v_add_f32_dpp v94, v94, v94 row_half_mirror row_mask:0xf bank_mask:0xf bound_ctrl:1
	s_nop 1
	v_add_f32_dpp v95, v95, v95 row_half_mirror row_mask:0xf bank_mask:0xf bound_ctrl:1
	s_nop 1
	v_add_f32_dpp v94, v94, v94 row_ror:8 row_mask:0xf bank_mask:0xf bound_ctrl:1
	v_mov_b32_e32 v96, v94
	s_nop 1
	v_add_f32_dpp v95, v95, v95 row_ror:8 row_mask:0xf bank_mask:0xf bound_ctrl:1
	v_mov_b32_e32 v97, v95
	s_nop 1
	v_permlane16_swap_b32_e32 v94, v96
	s_nop 1
	v_permlane16_swap_b32_e32 v95, v97
	v_add_f32_e32 v91, v94, v96
	v_add_f32_e32 v97, v95, v97
	v_mov_b32_e32 v93, v91
	v_mov_b32_e32 v92, v97
	s_nop 1
	v_permlane32_swap_b32_e32 v91, v93
	s_nop 1
	v_permlane32_swap_b32_e32 v97, v92
	v_add_f32_e32 v91, v91, v93
	v_add_f32_e32 v97, v97, v92
	v_mul_f32_e32 v91, 0x3fb8aa3b, v91
	v_mul_f32_e32 v97, 0x3fb8aa3b, v97
	v_exp_f32_e32 v91, v91
	v_exp_f32_e32 v97, v97
	s_nop 1
	v_sub_f32_e32 v4, v91, v97
	v_add_f32_e32 v4, 0x3e4ccccd, v4
	v_mov_b32_e32 v5, v4
	s_waitcnt vmcnt(23)
	v_mul_f32_e32 v24, v22, v25
	v_fmac_f32_e32 v67, v37, v9
	s_or_b32 s50, s50, s29
	v_mov_b32_dpp v24, v24 quad_perm:[1,0,3,2] row_mask:0xf bank_mask:0xf bound_ctrl:1
	v_fmac_f32_e32 v24, v22, v25
	s_mul_hi_u32 s51, s50, 0x210
	s_add_i32 s51, s51, s17
	v_add_f32_dpp v24, v24, v24 quad_perm:[2,3,0,1] row_mask:0xf bank_mask:0xf bound_ctrl:1
	s_mulk_i32 s50, 0x210
	s_add_u32 s50, s24, s50
	v_add_f32_dpp v24, v24, v24 row_half_mirror row_mask:0xf bank_mask:0xf bound_ctrl:1
	s_addc_u32 s51, s25, s51
	s_or_b32 s17, s66, s29
	v_add_f32_dpp v24, v24, v24 row_ror:8 row_mask:0xf bank_mask:0xf bound_ctrl:1
	v_mov_b32_e32 v25, v24
	s_nop 1
	v_permlane16_swap_b32_e32 v24, v25
	v_add_f32_e32 v24, v24, v25
	v_mov_b32_e32 v25, v24
	s_nop 1
	v_permlane32_swap_b32_e32 v24, v25
	v_add_f32_e32 v24, v24, v25
	v_fmac_f32_e32 v24, v37, v23
	v_cndmask_b32_e64 v68, v24, v30, s[6:7]
	s_waitcnt vmcnt(22)
	v_mul_f32_e32 v24, v22, v26
	s_mul_hi_u32 s52, s17, 0x210
	s_add_i32 s53, s52, s67
	v_mov_b32_dpp v24, v24 quad_perm:[1,0,3,2] row_mask:0xf bank_mask:0xf bound_ctrl:1
	v_fmac_f32_e32 v24, v22, v26
	s_mulk_i32 s17, 0x210
	s_add_u32 s52, s24, s17
	v_add_f32_dpp v24, v24, v24 quad_perm:[2,3,0,1] row_mask:0xf bank_mask:0xf bound_ctrl:1
	s_addc_u32 s53, s25, s53
	s_nop 0
	v_add_f32_dpp v24, v24, v24 row_half_mirror row_mask:0xf bank_mask:0xf bound_ctrl:1
	s_nop 1
	v_add_f32_dpp v24, v24, v24 row_ror:8 row_mask:0xf bank_mask:0xf bound_ctrl:1
	v_mov_b32_e32 v25, v24
	s_nop 1
	v_permlane16_swap_b32_e32 v24, v25
	v_add_f32_e32 v24, v24, v25
	v_mov_b32_e32 v25, v24
	s_nop 1
	v_permlane32_swap_b32_e32 v24, v25
	v_add_f32_e32 v24, v24, v25
	v_fmac_f32_e32 v24, v37, v28
	v_cndmask_b32_e64 v69, v24, v30, s[8:9]
	s_waitcnt vmcnt(21)
	v_mul_f32_e32 v24, v22, v27
	s_nop 1
	v_mov_b32_dpp v24, v24 quad_perm:[1,0,3,2] row_mask:0xf bank_mask:0xf bound_ctrl:1
	v_fmac_f32_e32 v24, v22, v27
	s_nop 1
	v_add_f32_dpp v22, v24, v24 quad_perm:[2,3,0,1] row_mask:0xf bank_mask:0xf bound_ctrl:1
	s_nop 1
	v_add_f32_dpp v22, v22, v22 row_half_mirror row_mask:0xf bank_mask:0xf bound_ctrl:1
	s_nop 1
	v_add_f32_dpp v22, v22, v22 row_ror:8 row_mask:0xf bank_mask:0xf bound_ctrl:1
	v_mov_b32_e32 v24, v22
	s_nop 1
	v_permlane16_swap_b32_e32 v22, v24
	v_add_f32_e32 v22, v22, v24
	v_mov_b32_e32 v24, v22
	s_nop 1
	v_permlane32_swap_b32_e32 v22, v24
	v_add_f32_e32 v22, v22, v24
	v_fmac_f32_e32 v22, v37, v29
	v_cndmask_b32_e64 v70, v30, v22, s[10:11]
	v_max_f32_e32 v22, v67, v68
	v_max3_f32 v22, v22, v69, v70
	s_waitcnt vmcnt(15)
	v_max3_f32 v22, v22, v14, v16
	s_waitcnt vmcnt(12)
	v_max3_f32 v22, v22, v18, v20
	s_waitcnt vmcnt(10)
	v_max3_f32 v22, v22, v38, v40
	s_waitcnt vmcnt(8)
	v_max3_f32 v71, v22, v42, v44
	v_sub_f32_e32 v14, v14, v71
	v_exp_f32_e32 v14, v14
	v_sub_f32_e32 v16, v16, v71
	v_exp_f32_e32 v16, v16
	v_sub_f32_e32 v18, v18, v71
	v_exp_f32_e32 v18, v18
	v_sub_f32_e32 v20, v20, v71
	v_fma_f32 v72, v14, v15, 0
	v_sub_f32_e32 v15, v38, v71
	v_exp_f32_e32 v20, v20
	v_exp_f32_e32 v22, v15
	v_sub_f32_e32 v15, v40, v71
	v_exp_f32_e32 v38, v15
	v_sub_f32_e32 v15, v42, v71
	v_fmac_f32_e32 v72, v16, v17
	v_exp_f32_e32 v40, v15
	v_sub_f32_e32 v15, v44, v71
	v_fmac_f32_e32 v72, v18, v19
	v_exp_f32_e32 v42, v15
	s_waitcnt vmcnt(7)
	v_pk_fma_f32 v[14:15], v[14:15], v[46:47], 0 op_sel_hi:[0,1,0]
	v_fmac_f32_e32 v72, v20, v21
	s_waitcnt vmcnt(6)
	v_pk_fma_f32 v[14:15], v[16:17], v[48:49], v[14:15] op_sel_hi:[0,1,1]
	v_sub_f32_e32 v16, v67, v71
	v_fmac_f32_e32 v72, v22, v39
	v_exp_f32_e32 v16, v16
	v_sub_f32_e32 v17, v68, v71
	v_fmac_f32_e32 v72, v38, v41
	s_waitcnt vmcnt(5)
	v_pk_fma_f32 v[14:15], v[18:19], v[50:51], v[14:15] op_sel_hi:[0,1,1]
	v_exp_f32_e32 v18, v17
	v_sub_f32_e32 v17, v69, v71
	v_fmac_f32_e32 v72, v40, v43
	s_waitcnt vmcnt(4)
	v_pk_fma_f32 v[14:15], v[20:21], v[52:53], v[14:15] op_sel_hi:[0,1,1]
	v_exp_f32_e32 v20, v17
	v_sub_f32_e32 v17, v70, v71
	v_fmac_f32_e32 v72, v42, v45
	s_waitcnt vmcnt(3)
	v_pk_fma_f32 v[14:15], v[22:23], v[54:55], v[14:15] op_sel_hi:[0,1,1]
	v_exp_f32_e32 v22, v17
	v_add_f32_e32 v17, v16, v72
	v_add_f32_e32 v17, v18, v17
	v_add_f32_e32 v17, v20, v17
	v_add_f32_e32 v17, v22, v17
	s_waitcnt vmcnt(2)
	v_pk_fma_f32 v[14:15], v[38:39], v[56:57], v[14:15] op_sel_hi:[0,1,1]
	v_lshl_add_u64 v[38:39], v[12:13], 0, s[12:13]
	v_div_scale_f32 v19, s[12:13], v17, v17, 1.0
	s_or_b32 s12, s56, s29
	s_mul_hi_u32 s13, s12, 0x210
	s_add_i32 s13, s13, s20
	s_mulk_i32 s12, 0x210
	s_add_u32 s12, s24, s12
	s_addc_u32 s13, s25, s13
	s_or_b32 s17, s58, s29
	s_mul_hi_u32 s20, s17, 0x210
	s_add_i32 s20, s20, s57
	s_mulk_i32 s17, 0x210
	s_waitcnt vmcnt(1)
	v_pk_fma_f32 v[14:15], v[40:41], v[58:59], v[14:15] op_sel_hi:[0,1,1]
	v_lshl_add_u64 v[40:41], v[12:13], 0, s[22:23]
	s_add_u32 s22, s24, s17
	s_addc_u32 s23, s25, s20
	s_or_b32 s17, s60, s29
	s_mul_hi_u32 s20, s17, 0x210
	s_add_i32 s20, s20, s59
	s_mulk_i32 s17, 0x210
	s_waitcnt vmcnt(0)
	v_pk_fma_f32 v[14:15], v[42:43], v[60:61], v[14:15] op_sel_hi:[0,1,1]
	v_lshl_add_u64 v[42:43], v[12:13], 0, s[44:45]
	s_add_u32 s44, s24, s17
	s_addc_u32 s45, s25, s20
	s_or_b32 s17, s62, s29
	s_mul_hi_u32 s20, s17, 0x210
	v_rcp_f32_e32 v21, v19
	s_add_i32 s20, s20, s61
	s_mulk_i32 s17, 0x210
	v_lshl_add_u64 v[12:13], v[12:13], 0, s[48:49]
	s_add_u32 s48, s24, s17
	s_addc_u32 s49, s25, s20
	s_or_b32 s17, s64, s29
	s_mul_hi_u32 s20, s17, 0x210
	v_fma_f32 v44, -v19, v21, 1.0
	s_add_i32 s20, s20, s63
	s_mulk_i32 s17, 0x210
	v_fmac_f32_e32 v21, v44, v21
	v_div_scale_f32 v44, vcc, 1.0, v17, 1.0
	s_add_u32 s56, s24, s17
	v_mul_f32_e32 v73, v44, v21
	s_addc_u32 s57, s25, s20
	s_or_b32 s17, s54, s29
	global_load_dwordx2 v[24:25], v1, s[50:51]
	global_load_dwordx2 v[26:27], v1, s[52:53]
	v_fma_f32 v45, -v19, v73, v44
	v_mul_f32_e32 v56, v66, v65
	s_mul_hi_u32 s20, s17, 0x210
	v_fmac_f32_e32 v73, v45, v21
	s_add_i32 s20, s20, s55
	s_mulk_i32 s17, 0x210
	v_mov_b32_dpp v56, v56 quad_perm:[1,0,3,2] row_mask:0xf bank_mask:0xf bound_ctrl:1
	v_fma_f32 v19, -v19, v73, v44
	global_load_dwordx2 v[44:45], v1, s[12:13]
	global_load_dwordx2 v[46:47], v1, s[22:23]
	global_load_dwordx2 v[48:49], v1, s[44:45]
	global_load_dwordx2 v[50:51], v1, s[48:49]
	s_add_u32 s54, s24, s17
	v_fmac_f32_e32 v56, v66, v65
	s_addc_u32 s55, s25, s20
	global_load_dwordx2 v[52:53], v1, s[56:57]
	global_load_dwordx2 v[54:55], v1, s[54:55]
	v_add_f32_dpp v56, v56, v56 quad_perm:[2,3,0,1] row_mask:0xf bank_mask:0xf bound_ctrl:1
	v_div_fmas_f32 v19, v19, v21, v73
	v_div_fixup_f32 v80, v19, v17, 1.0
	v_add_f32_dpp v56, v56, v56 row_half_mirror row_mask:0xf bank_mask:0xf bound_ctrl:1
	s_nop 1
	v_add_f32_dpp v56, v56, v56 row_ror:8 row_mask:0xf bank_mask:0xf bound_ctrl:1
	v_mov_b32_e32 v57, v56
	s_nop 1
	v_permlane16_swap_b32_e32 v56, v57
	v_add_f32_e32 v56, v56, v57
	v_mov_b32_e32 v57, v56
	s_nop 1
	v_permlane32_swap_b32_e32 v56, v57
	v_add_f32_e32 v72, v56, v57
	v_mul_f32_e32 v56, v66, v64
	v_fmac_f32_e32 v72, v37, v9
	s_nop 0
	v_mov_b32_dpp v56, v56 quad_perm:[1,0,3,2] row_mask:0xf bank_mask:0xf bound_ctrl:1
	v_fmac_f32_e32 v56, v66, v64
	s_nop 1
	v_add_f32_dpp v56, v56, v56 quad_perm:[2,3,0,1] row_mask:0xf bank_mask:0xf bound_ctrl:1
	s_nop 1
	v_add_f32_dpp v56, v56, v56 row_half_mirror row_mask:0xf bank_mask:0xf bound_ctrl:1
	s_nop 1
	v_add_f32_dpp v56, v56, v56 row_ror:8 row_mask:0xf bank_mask:0xf bound_ctrl:1
	v_mov_b32_e32 v57, v56
	s_nop 1
	v_permlane16_swap_b32_e32 v56, v57
	v_add_f32_e32 v56, v56, v57
	v_mov_b32_e32 v57, v56
	s_nop 1
	v_permlane32_swap_b32_e32 v56, v57
	v_add_f32_e32 v56, v56, v57
	v_fmac_f32_e32 v56, v37, v23
	v_cndmask_b32_e64 v74, v56, v30, s[6:7]
	v_mul_f32_e32 v56, v66, v63
	s_nop 1
	v_mov_b32_dpp v56, v56 quad_perm:[1,0,3,2] row_mask:0xf bank_mask:0xf bound_ctrl:1
	v_fmac_f32_e32 v56, v66, v63
	s_nop 1
	v_add_f32_dpp v56, v56, v56 quad_perm:[2,3,0,1] row_mask:0xf bank_mask:0xf bound_ctrl:1
	s_nop 1
	v_add_f32_dpp v56, v56, v56 row_half_mirror row_mask:0xf bank_mask:0xf bound_ctrl:1
	s_nop 1
	v_add_f32_dpp v56, v56, v56 row_ror:8 row_mask:0xf bank_mask:0xf bound_ctrl:1
	v_mov_b32_e32 v57, v56
	s_nop 1
	v_permlane16_swap_b32_e32 v56, v57
	v_add_f32_e32 v56, v56, v57
	v_mov_b32_e32 v57, v56
	s_nop 1
	v_permlane32_swap_b32_e32 v56, v57
	v_add_f32_e32 v56, v56, v57
	v_fmac_f32_e32 v56, v37, v28
	v_cndmask_b32_e64 v75, v56, v30, s[8:9]
	v_mul_f32_e32 v56, v66, v62
	s_nop 1
	v_mov_b32_dpp v56, v56 quad_perm:[1,0,3,2] row_mask:0xf bank_mask:0xf bound_ctrl:1
	v_fmac_f32_e32 v56, v66, v62
	s_nop 1
	v_add_f32_dpp v56, v56, v56 quad_perm:[2,3,0,1] row_mask:0xf bank_mask:0xf bound_ctrl:1
	s_nop 1
	v_add_f32_dpp v56, v56, v56 row_half_mirror row_mask:0xf bank_mask:0xf bound_ctrl:1
	s_nop 1
	v_add_f32_dpp v76, v56, v56 row_ror:8 row_mask:0xf bank_mask:0xf bound_ctrl:1
	global_load_dwordx2 v[38:39], v[38:39], off
	s_nop 0
	global_load_dwordx2 v[40:41], v[40:41], off
	s_nop 0
	global_load_dwordx2 v[42:43], v[42:43], off
	s_nop 0
	global_load_dwordx2 v[12:13], v[12:13], off
	s_nop 0
	global_load_dwordx2 v[56:57], v31, s[50:51] offset:16
	global_load_dwordx2 v[58:59], v31, s[52:53] offset:16
	global_load_dwordx2 v[60:61], v31, s[12:13] offset:16
	global_load_dwordx2 v[62:63], v31, s[22:23] offset:16
	global_load_dwordx2 v[64:65], v31, s[44:45] offset:16
	global_load_dwordx2 v[66:67], v31, s[48:49] offset:16
	global_load_dwordx2 v[68:69], v31, s[56:57] offset:16
	global_load_dwordx2 v[70:71], v31, s[54:55] offset:16
	v_mov_b32_e32 v77, v76
	s_nop 1
	v_permlane16_swap_b32_e32 v76, v77
	v_add_f32_e32 v76, v76, v77
	v_mov_b32_e32 v77, v76
	s_nop 1
	v_permlane32_swap_b32_e32 v76, v77
	v_add_f32_e32 v76, v76, v77
	v_fmac_f32_e32 v76, v37, v29
	v_cndmask_b32_e64 v37, v30, v76, s[10:11]
	v_max_f32_e32 v76, v72, v74
	v_max3_f32 v76, v76, v75, v37
	s_waitcnt vmcnt(18)
	v_max3_f32 v76, v76, v24, v26
	s_waitcnt vmcnt(16)
	v_max3_f32 v76, v76, v44, v46
	s_waitcnt vmcnt(14)
	v_max3_f32 v76, v76, v48, v50
	s_waitcnt vmcnt(12)
	v_max3_f32 v77, v76, v52, v54
	v_sub_f32_e32 v24, v24, v77
	v_exp_f32_e32 v24, v24
	v_sub_f32_e32 v26, v26, v77
	v_exp_f32_e32 v26, v26
	v_sub_f32_e32 v44, v44, v77
	v_exp_f32_e32 v44, v44
	v_sub_f32_e32 v46, v46, v77
	v_fma_f32 v25, v24, v25, 0
	v_exp_f32_e32 v46, v46
	v_fmac_f32_e32 v25, v26, v27
	v_sub_f32_e32 v27, v48, v77
	v_exp_f32_e32 v48, v27
	v_sub_f32_e32 v27, v50, v77
	v_exp_f32_e32 v50, v27
	v_sub_f32_e32 v27, v52, v77
	v_fmac_f32_e32 v25, v44, v45
	v_exp_f32_e32 v52, v27
	v_sub_f32_e32 v27, v54, v77
	v_fmac_f32_e32 v25, v46, v47
	v_exp_f32_e32 v54, v27
	v_sub_f32_e32 v27, v72, v77
	v_fmac_f32_e32 v25, v48, v49
	v_exp_f32_e32 v72, v27
	v_sub_f32_e32 v27, v74, v77
	v_fmac_f32_e32 v25, v50, v51
	v_exp_f32_e32 v74, v27
	v_sub_f32_e32 v27, v75, v77
	v_fmac_f32_e32 v25, v52, v53
	v_exp_f32_e32 v76, v27
	v_sub_f32_e32 v27, v37, v77
	v_fmac_f32_e32 v25, v54, v55
	v_exp_f32_e32 v78, v27
	v_add_f32_e32 v25, v72, v25
	v_add_f32_e32 v25, v74, v25
	v_add_f32_e32 v25, v76, v25
	v_add_f32_e32 v25, v78, v25
	v_div_scale_f32 v27, s[12:13], v25, v25, 1.0
	v_rcp_f32_e32 v37, v27
	s_nop 0
	v_fma_f32 v17, -v27, v37, 1.0
	v_fmac_f32_e32 v37, v17, v37
	v_div_scale_f32 v17, vcc, 1.0, v25, 1.0
	v_mul_f32_e32 v19, v17, v37
	v_fma_f32 v21, -v27, v19, v17
	v_fmac_f32_e32 v19, v21, v37
	v_fma_f32 v17, -v27, v19, v17
	v_div_fmas_f32 v17, v17, v37, v19
	v_div_fixup_f32 v82, v17, v25, 1.0
	s_waitcnt vmcnt(11)
	v_pk_fma_f32 v[14:15], v[16:17], v[38:39], v[14:15] op_sel_hi:[0,1,1]
	s_waitcnt vmcnt(10)
	v_pk_fma_f32 v[14:15], v[18:19], v[40:41], v[14:15] op_sel_hi:[0,1,1]
	s_waitcnt vmcnt(9)
	v_pk_fma_f32 v[14:15], v[20:21], v[42:43], v[14:15] op_sel_hi:[0,1,1]
	s_waitcnt vmcnt(8)
	v_pk_fma_f32 v[14:15], v[22:23], v[12:13], v[14:15] op_sel_hi:[0,1,1]
	s_waitcnt vmcnt(7)
	v_pk_fma_f32 v[16:17], v[24:25], v[56:57], 0 op_sel_hi:[0,1,0]
	s_waitcnt vmcnt(6)
	v_pk_fma_f32 v[16:17], v[26:27], v[58:59], v[16:17] op_sel_hi:[0,1,1]
	s_waitcnt vmcnt(5)
	v_pk_fma_f32 v[16:17], v[44:45], v[60:61], v[16:17] op_sel_hi:[0,1,1]
	s_waitcnt vmcnt(4)
	v_pk_fma_f32 v[16:17], v[46:47], v[62:63], v[16:17] op_sel_hi:[0,1,1]
	s_waitcnt vmcnt(3)
	v_pk_fma_f32 v[16:17], v[48:49], v[64:65], v[16:17] op_sel_hi:[0,1,1]
	s_waitcnt vmcnt(2)
	v_pk_fma_f32 v[16:17], v[50:51], v[66:67], v[16:17] op_sel_hi:[0,1,1]
	s_waitcnt vmcnt(1)
	v_pk_fma_f32 v[16:17], v[52:53], v[68:69], v[16:17] op_sel_hi:[0,1,1]
	s_waitcnt vmcnt(0)
	v_pk_fma_f32 v[16:17], v[54:55], v[70:71], v[16:17] op_sel_hi:[0,1,1]
	v_pk_fma_f32 v[16:17], v[72:73], v[38:39], v[16:17] op_sel_hi:[0,1,1]
	v_pk_fma_f32 v[16:17], v[74:75], v[40:41], v[16:17] op_sel_hi:[0,1,1]
	v_pk_fma_f32 v[16:17], v[76:77], v[42:43], v[16:17] op_sel_hi:[0,1,1]
	v_pk_fma_f32 v[12:13], v[78:79], v[12:13], v[16:17] op_sel_hi:[0,1,1]
	v_pk_mul_f32 v[12:13], v[82:83], v[12:13] op_sel_hi:[0,1]
	v_pk_mul_f32 v[12:13], v[4:5], v[12:13]
	s_nop 0
	v_pk_fma_f32 v[12:13], v[80:81], v[14:15], v[12:13] op_sel_hi:[0,1,1] neg_lo:[0,0,1] neg_hi:[0,0,1]
	v_pk_mul_f32 v[14:15], v[12:13], v[12:13]
	s_nop 0
	v_add_f32_e32 v14, v14, v15
	s_nop 1
	v_add_f32_dpp v14, v14, v14 quad_perm:[1,0,3,2] row_mask:0xf bank_mask:0xf bound_ctrl:1
	s_nop 1
	v_add_f32_dpp v14, v14, v14 quad_perm:[2,3,0,1] row_mask:0xf bank_mask:0xf bound_ctrl:1
	s_nop 1
	v_add_f32_dpp v14, v14, v14 row_half_mirror row_mask:0xf bank_mask:0xf bound_ctrl:1
	s_nop 1
	v_add_f32_dpp v14, v14, v14 row_ror:8 row_mask:0xf bank_mask:0xf bound_ctrl:1
	v_mov_b32_e32 v15, v14
	s_nop 1
	v_permlane16_swap_b32_e32 v14, v15
	v_add_f32_e32 v14, v14, v15
	v_mov_b32_e32 v15, v14
	s_nop 1
	v_permlane32_swap_b32_e32 v14, v15
	v_add_f32_e32 v14, v14, v15
	v_fmamk_f32 v14, v14, 0x3c000000, v32
	v_mul_f32_e32 v15, 0x4f800000, v14
	v_cmp_gt_f32_e32 vcc, s30, v14
	s_nop 1
	v_cndmask_b32_e32 v14, v14, v15, vcc
	v_sqrt_f32_e32 v15, v14
	s_nop 0
	v_add_u32_e32 v16, -1, v15
	v_fma_f32 v17, -v16, v15, v14
	v_cmp_ge_f32_e64 s[12:13], 0, v17
	v_add_u32_e32 v17, 1, v15
	s_nop 0
	v_cndmask_b32_e64 v16, v15, v16, s[12:13]
	v_fma_f32 v15, -v17, v15, v14
	v_cmp_lt_f32_e64 s[12:13], 0, v15
	s_nop 1
	v_cndmask_b32_e64 v15, v16, v17, s[12:13]
	v_mul_f32_e32 v16, 0x37800000, v15
	v_cndmask_b32_e32 v15, v15, v16, vcc
	v_cmp_class_f32_e32 vcc, v14, v33
	s_nop 1
	v_cndmask_b32_e32 v14, v15, v14, vcc
	v_div_scale_f32 v15, s[12:13], v14, v14, s31
	v_rcp_f32_e32 v16, v15
	s_add_i32 s12, s16, 0x4000
	s_ashr_i32 s13, s12, 31
	s_lshl_b64 s[12:13], s[12:13], 11
	v_fma_f32 v17, -v15, v16, 1.0
	v_fmac_f32_e32 v16, v17, v16
	v_div_scale_f32 v17, vcc, s31, v14, s31
	v_mul_f32_e32 v18, v17, v16
	v_fma_f32 v19, -v15, v18, v17
	v_fmac_f32_e32 v18, v19, v16
	v_fma_f32 v15, -v15, v18, v17
	v_div_fmas_f32 v15, v15, v16, v18
	v_div_fixup_f32 v14, v15, v14, s31
	v_pk_mul_f32 v[12:13], v[12:13], v[14:15] op_sel_hi:[1,0]
	s_add_u32 s12, s26, s12
	v_pk_mul_f32 v[12:13], v[2:3], v[12:13]
	s_addc_u32 s13, s27, s13
	v_and_b32_sdwa v15, v12, v36 dst_sel:DWORD dst_unused:UNUSED_PAD src0_sel:WORD_1 src1_sel:DWORD
	s_lshl_b32 s16, s76, 8
	v_and_b32_sdwa v14, v13, v36 dst_sel:DWORD dst_unused:UNUSED_PAD src0_sel:WORD_1 src1_sel:DWORD
	v_add3_u32 v12, v12, v15, s41
	s_add_u32 s12, s12, s16
	v_add3_u32 v13, v13, v14, s41
	v_lshrrev_b32_e32 v12, 16, v12
	s_addc_u32 s13, s13, 0
	s_add_i32 s75, s75, s34
	v_and_or_b32 v12, v13, s72, v12
	v_lshlrev_b32_e32 v13, 1, v8
	s_cmpk_gt_i32 s75, 0x1ff
	global_store_dword v13, v12, s[12:13] sc1
	s_cbranch_scc1 .LBB0_657
